# outproj gate loop: steady-state scalar-base DMA (saddr form) for K-tiles 3..15
# speedup vs baseline: 1.0986x; 1.0040x over previous
.LBB0_844:
	s_mul_i32 s27, s11, 0xc000
	v_or_b32_e32 v92, s27, v220
	v_add_u32_e32 v96, s27, v219
	ds_read_b128 v[12:15], v92 offset:32768
	ds_read_b128 v[28:31], v92 offset:34816
	ds_read_b128 v[36:39], v96
	ds_read_b128 v[40:43], v96 offset:2048
	ds_read_b128 v[48:51], v96 offset:4096
	ds_read_b128 v[52:55], v96 offset:6144
	ds_read_b128 v[60:63], v96 offset:8192
	ds_read_b128 v[68:71], v96 offset:10240
	ds_read_b128 v[72:75], v96 offset:12288
	ds_read_b128 v[80:83], v96 offset:14336
	s_cmp_eq_u32 s19, 0
	s_cbranch_scc1 .Lpg844_first
	s_cmp_gt_u32 s19, 13
	s_cbranch_scc1 .Lpg844_late
	v_mfma_f32_16x16x32_bf16 v[124:127], v[84:87], v[108:111], v[124:127]
	s_mul_i32 s22, s45, 0xc000
	v_add_u32_e32 v93, s22, v217
	v_mfma_f32_16x16x32_bf16 v[120:123], v[104:107], v[108:111], v[120:123]
	s_nop 0
	v_readfirstlane_b32 s22, v93
	s_nop 1
	s_add_u32 m0, s22, 0x0
	v_mfma_f32_16x16x32_bf16 v[112:115], v[84:87], v[116:119], v[112:115]
	global_load_lds_dwordx4 v249, s[98:99]
	s_add_u32 m0, s22, 0x2000
	v_mfma_f32_16x16x32_bf16 v[100:103], v[104:107], v[116:119], v[100:103]
	global_load_lds_dwordx4 v250, s[98:99]
	s_add_u32 m0, s22, 0x4000
	v_mfma_f32_16x16x32_bf16 v[88:91], v[84:87], v[222:225], v[88:91]
	global_load_lds_dwordx4 v251, s[98:99]
	s_add_u32 m0, s22, 0x6000
	v_mfma_f32_16x16x32_bf16 v[76:79], v[104:107], v[222:225], v[76:79]
	global_load_lds_dwordx4 v254, s[98:99]
	s_add_u32 m0, s22, 0x8000
	v_mfma_f32_16x16x32_bf16 v[64:67], v[84:87], v[226:229], v[64:67]
	global_load_lds_dwordx4 v249, s[100:101]
	s_add_u32 m0, s22, 0xa000
	v_mfma_f32_16x16x32_bf16 v[56:59], v[104:107], v[226:229], v[56:59]
	global_load_lds_dwordx4 v250, s[100:101]
	v_mfma_f32_16x16x32_bf16 v[44:47], v[84:87], v[230:233], v[44:47]
	s_add_u32 s98, s98, 0x80
	s_addc_u32 s99, s99, 0
	s_add_u32 s100, s100, 0x80
	s_addc_u32 s101, s101, 0
	v_mfma_f32_16x16x32_bf16 v[32:35], v[104:107], v[230:233], v[32:35]
	v_mfma_f32_16x16x32_bf16 v[24:27], v[84:87], v[234:237], v[24:27]
	v_mfma_f32_16x16x32_bf16 v[20:23], v[104:107], v[234:237], v[20:23]
	v_mfma_f32_16x16x32_bf16 v[16:19], v[84:87], v[238:241], v[16:19]
	v_mfma_f32_16x16x32_bf16 v[8:11], v[104:107], v[238:241], v[8:11]
	v_mfma_f32_16x16x32_bf16 v[4:7], v[84:87], v[242:245], v[4:7]
	v_mfma_f32_16x16x32_bf16 v[0:3], v[104:107], v[242:245], v[0:3]
	s_branch .Lpg844_main
; DI void phase_outproj(const Params& P, char* shm) {
;     ...
;     for (int x = 0; x < 4; ++x) {
; #pragma unroll
;       for (int m = 0; m < 8; ++m) { acc[m][0] = f32x4{0.f, 0.f, 0.f, 0.f}; acc[m][1] = f32x4{0.f, 0.f, 0.f, 0.f}; }
; #pragma clang loop unroll(disable)
;       for (int r = 0; r < 16; ++r) {
;         O_ISSUE(x, r + 2, nxt);
;         O_COMPUTE();
;         asm volatile("s_waitcnt vmcnt(6)" ::: "memory");
;         O_ROTATE();
.Lpg844_late:
	v_mfma_f32_16x16x32_bf16 v[124:127], v[84:87], v[108:111], v[124:127]
	s_cmp_lt_u32 s19, 14
	s_cselect_b64 vcc, -1, 0
	s_and_b64 s[20:21], vcc, exec
	s_cselect_b32 s22, 2, -14
	v_mfma_f32_16x16x32_bf16 v[120:123], v[104:107], v[108:111], v[120:123]
	s_cselect_b32 s21, s9, s13
	s_cselect_b32 s20, s8, s12
	s_add_i32 s24, s22, s19
	s_mul_i32 s22, s45, 0xc000
	v_mfma_f32_16x16x32_bf16 v[112:115], v[84:87], v[116:119], v[112:115]
	v_add_u32_e32 v93, s22, v217
	v_cndmask_b32_e32 v97, v218, v128, vcc
	v_readfirstlane_b32 s22, v93
	v_lshl_add_u32 v94, s24, 6, v97
	v_mfma_f32_16x16x32_bf16 v[100:103], v[104:107], v[116:119], v[100:103]
	s_mov_b32 m0, s22
	s_and_b64 s[22:23], vcc, exec
	v_ashrrev_i32_e32 v95, 31, v94
	s_cselect_b32 s22, 10, 9
	v_mfma_f32_16x16x32_bf16 v[88:91], v[84:87], v[222:225], v[88:91]
	v_lshlrev_b64 v[94:95], 1, v[94:95]
	s_lshl_b32 s23, 1, s22
	v_lshl_add_u64 v[98:99], s[20:21], 0, v[94:95]
	s_add_i32 s23, s24, s23
	v_mfma_f32_16x16x32_bf16 v[76:79], v[104:107], v[222:225], v[76:79]
	global_load_lds_dwordx4 v[98:99], off
	v_lshl_add_u32 v98, s23, 6, v97
	v_add_u32_e32 v248, 0x2000, v93
	v_ashrrev_i32_e32 v99, 31, v98
	v_mfma_f32_16x16x32_bf16 v[64:67], v[84:87], v[226:229], v[64:67]
	v_readfirstlane_b32 s23, v248
	v_lshlrev_b64 v[98:99], 1, v[98:99]
	s_mov_b32 m0, s23
	s_lshl_b32 s23, 2, s22
	v_mfma_f32_16x16x32_bf16 v[56:59], v[104:107], v[226:229], v[56:59]
	v_lshl_add_u64 v[246:247], s[20:21], 0, v[98:99]
	s_add_i32 s23, s24, s23
	global_load_lds_dwordx4 v[246:247], off
	v_lshl_add_u32 v246, s23, 6, v97
	v_mfma_f32_16x16x32_bf16 v[44:47], v[84:87], v[230:233], v[44:47]
	v_add_u32_e32 v248, 0x4000, v93
	v_ashrrev_i32_e32 v247, 31, v246
	v_readfirstlane_b32 s23, v248
	s_lshl_b32 s22, 3, s22
	v_mfma_f32_16x16x32_bf16 v[32:35], v[104:107], v[230:233], v[32:35]
	v_lshl_add_u64 v[246:247], v[246:247], 1, s[20:21]
	s_mov_b32 m0, s23
	s_add_i32 s24, s24, s22
	global_load_lds_dwordx4 v[246:247], off
	v_mfma_f32_16x16x32_bf16 v[24:27], v[84:87], v[234:237], v[24:27]
	v_lshl_add_u32 v246, s24, 6, v97
	v_ashrrev_i32_e32 v247, 31, v246
	v_add_u32_e32 v97, 0x6000, v93
	v_lshl_add_u64 v[246:247], v[246:247], 1, s[20:21]
	v_mfma_f32_16x16x32_bf16 v[20:23], v[104:107], v[234:237], v[20:23]
	v_readfirstlane_b32 s20, v97
	s_mov_b32 m0, s20
	s_and_b64 s[20:21], vcc, exec
	global_load_lds_dwordx4 v[246:247], off
	v_mfma_f32_16x16x32_bf16 v[16:19], v[84:87], v[238:241], v[16:19]
	v_add_u32_e32 v246, 0x8000, v93
	s_cselect_b32 s21, s17, s15
	s_cselect_b32 s20, s16, s14
	v_readfirstlane_b32 s22, v246
	v_mfma_f32_16x16x32_bf16 v[8:11], v[104:107], v[238:241], v[8:11]
	v_lshl_add_u64 v[94:95], s[20:21], 0, v[94:95]
	s_mov_b32 m0, s22
	s_nop 0
	global_load_lds_dwordx4 v[94:95], off
	v_mfma_f32_16x16x32_bf16 v[4:7], v[84:87], v[242:245], v[4:7]
	v_lshl_add_u64 v[94:95], s[20:21], 0, v[98:99]
	v_add_u32_e32 v98, 0xa000, v93
	s_nop 0
	v_readfirstlane_b32 s20, v98
	v_mfma_f32_16x16x32_bf16 v[0:3], v[104:107], v[242:245], v[0:3]
	s_mov_b32 m0, s20
	global_load_lds_dwordx4 v[94:95], off
	s_branch .Lpg844_main
.Lpg844_first:
	s_cmp_lt_u32 s19, 14
	s_cselect_b64 vcc, -1, 0
	s_and_b64 s[20:21], vcc, exec
	s_cselect_b32 s22, 2, -14
	s_cselect_b32 s21, s9, s13
	s_cselect_b32 s20, s8, s12
	s_add_i32 s24, s22, s19
	s_mul_i32 s22, s45, 0xc000
	v_add_u32_e32 v93, s22, v217
	v_cndmask_b32_e32 v97, v218, v128, vcc
	v_readfirstlane_b32 s22, v93
	v_lshl_add_u32 v94, s24, 6, v97
	s_mov_b32 m0, s22
	s_and_b64 s[22:23], vcc, exec
	v_ashrrev_i32_e32 v95, 31, v94
	s_cselect_b32 s22, 10, 9
	v_lshlrev_b64 v[94:95], 1, v[94:95]
	s_lshl_b32 s23, 1, s22
	v_lshl_add_u64 v[98:99], s[20:21], 0, v[94:95]
	v_subrev_u32_e32 v249, s20, v98
	s_add_i32 s23, s24, s23
	global_load_lds_dwordx4 v[98:99], off
	v_lshl_add_u32 v98, s23, 6, v97
	v_add_u32_e32 v248, 0x2000, v93
	v_ashrrev_i32_e32 v99, 31, v98
	v_readfirstlane_b32 s23, v248
	v_lshlrev_b64 v[98:99], 1, v[98:99]
	s_mov_b32 m0, s23
	s_lshl_b32 s23, 2, s22
	v_lshl_add_u64 v[246:247], s[20:21], 0, v[98:99]
	v_subrev_u32_e32 v250, s20, v246
	s_add_i32 s23, s24, s23
	global_load_lds_dwordx4 v[246:247], off
	v_lshl_add_u32 v246, s23, 6, v97
	v_add_u32_e32 v248, 0x4000, v93
	v_ashrrev_i32_e32 v247, 31, v246
	v_readfirstlane_b32 s23, v248
	s_lshl_b32 s22, 3, s22
	v_lshl_add_u64 v[246:247], v[246:247], 1, s[20:21]
	v_subrev_u32_e32 v251, s20, v246
	s_mov_b32 m0, s23
	s_add_i32 s24, s24, s22
	global_load_lds_dwordx4 v[246:247], off
	v_lshl_add_u32 v246, s24, 6, v97
	v_ashrrev_i32_e32 v247, 31, v246
	v_add_u32_e32 v97, 0x6000, v93
	v_lshl_add_u64 v[246:247], v[246:247], 1, s[20:21]
	v_subrev_u32_e32 v254, s20, v246
	v_readfirstlane_b32 s20, v97
	s_mov_b32 m0, s20
	s_and_b64 s[20:21], vcc, exec
	global_load_lds_dwordx4 v[246:247], off
	v_add_u32_e32 v246, 0x8000, v93
	s_cselect_b32 s21, s17, s15
	s_cselect_b32 s20, s16, s14
	v_readfirstlane_b32 s22, v246
	v_lshl_add_u64 v[94:95], s[20:21], 0, v[94:95]
	s_mov_b32 m0, s22
	s_nop 0
	global_load_lds_dwordx4 v[94:95], off
	v_lshl_add_u64 v[94:95], s[20:21], 0, v[98:99]
	v_add_u32_e32 v98, 0xa000, v93
	s_nop 0
	v_readfirstlane_b32 s20, v98
	s_mov_b32 m0, s20
	global_load_lds_dwordx4 v[94:95], off
	s_add_u32 s98, s8, 0x80
	s_addc_u32 s99, s9, 0
	s_add_u32 s100, s16, 0x80
	s_addc_u32 s101, s17, 0

; __global__ void __launch_bounds__(512) fwd_megakernel(Params P) {
;   __shared__ __attribute__((aligned(1024))) char shm[148480];
	.amdhsa_kernel _Z14fwd_megakernel6Params
		.amdhsa_group_segment_fixed_size 148480
		.amdhsa_private_segment_fixed_size 0
		.amdhsa_kernarg_size 472
		.amdhsa_user_sgpr_count 2
		.amdhsa_user_sgpr_dispatch_ptr 0
		.amdhsa_user_sgpr_queue_ptr 0
		.amdhsa_user_sgpr_kernarg_segment_ptr 1
		.amdhsa_user_sgpr_dispatch_id 0
		.amdhsa_user_sgpr_kernarg_preload_length 0
		.amdhsa_user_sgpr_kernarg_preload_offset 0
		.amdhsa_user_sgpr_private_segment_size 0
		.amdhsa_uses_dynamic_stack 0
		.amdhsa_enable_private_segment 0
		.amdhsa_system_sgpr_workgroup_id_x 1
		.amdhsa_system_sgpr_workgroup_id_y 0
		.amdhsa_system_sgpr_workgroup_id_z 0
		.amdhsa_system_sgpr_workgroup_info 0
		.amdhsa_system_vgpr_workitem_id 2
		.amdhsa_next_free_vgpr 256
		.amdhsa_next_free_sgpr 102
		.amdhsa_accum_offset 256
		.amdhsa_reserve_vcc 1
		.amdhsa_float_round_mode_32 0
		.amdhsa_float_round_mode_16_64 0
		.amdhsa_float_denorm_mode_32 3
		.amdhsa_float_denorm_mode_16_64 3
		.amdhsa_dx10_clamp 1
		.amdhsa_ieee_mode 1
		.amdhsa_fp16_overflow 0
		.amdhsa_tg_split 0
		.amdhsa_exception_fp_ieee_invalid_op 0
		.amdhsa_exception_fp_denorm_src 0
		.amdhsa_exception_fp_ieee_div_zero 0
		.amdhsa_exception_fp_ieee_overflow 0
		.amdhsa_exception_fp_ieee_underflow 0
		.amdhsa_exception_fp_ieee_inexact 0
		.amdhsa_exception_int_div_zero 0
	.end_amdhsa_kernel

; __global__ void __launch_bounds__(512) fwd_megakernel(Params P) {
;   __shared__ __attribute__((aligned(1024))) char shm[148480];
amdhsa.kernels:
  - .agpr_count:     0
    .args:
      - .offset:         0
        .size:           216
        .value_kind:     by_value
      - .offset:         216
        .size:           4
        .value_kind:     hidden_block_count_x
      - .offset:         220
        .size:           4
        .value_kind:     hidden_block_count_y
      - .offset:         224
        .size:           4
        .value_kind:     hidden_block_count_z
      - .offset:         228
        .size:           2
        .value_kind:     hidden_group_size_x
      - .offset:         230
        .size:           2
        .value_kind:     hidden_group_size_y
      - .offset:         232
        .size:           2
        .value_kind:     hidden_group_size_z
      - .offset:         234
        .size:           2
        .value_kind:     hidden_remainder_x
      - .offset:         236
        .size:           2
        .value_kind:     hidden_remainder_y
      - .offset:         238
        .size:           2
        .value_kind:     hidden_remainder_z
      - .offset:         256
        .size:           8
        .value_kind:     hidden_global_offset_x
      - .offset:         264
        .size:           8
        .value_kind:     hidden_global_offset_y
      - .offset:         272
        .size:           8
        .value_kind:     hidden_global_offset_z
      - .offset:         280
        .size:           2
        .value_kind:     hidden_grid_dims
      - .offset:         304
        .size:           8
        .value_kind:     hidden_multigrid_sync_arg
    .group_segment_fixed_size: 148480
    .kernarg_segment_align: 8
    .kernarg_segment_size: 472
    .language:       OpenCL C
    .language_version:
      - 2
      - 0
    .max_flat_workgroup_size: 512
    .name:           _Z14fwd_megakernel6Params
    .private_segment_fixed_size: 0
    .sgpr_count:     108
    .sgpr_spill_count: 116
    .symbol:         _Z14fwd_megakernel6Params.kd
    .uniform_work_group_size: 1
    .uses_dynamic_stack: false
    .vgpr_count:     256
    .vgpr_spill_count: 0
    .wavefront_size: 64
